# GEMM K-loops: dropped the priority 0/1 flip in the middle of each 32-MFMA compute segment (12 sites); on top of the norm-phase loop rewrite
# speedup vs baseline: 1.0082x; 1.0082x over previous
; #define PG8_STAGE(bufoff, gbase, voff) do { _Pragma("unroll") for (int _i = 0; _i < 2; ++_i) \
;         __builtin_amdgcn_global_load_lds((const unsigned*)((const char*)(gbase) + (voff)[_i]), (PG8_LAS unsigned*)(lds + (bufoff) + ldsw + _i * 8192), 16, 0, 0); } while (0)
; #define PG8_LDA(dst, b, h) do { _Pragma("unroll") for (int m = 0; m < 4; ++m) _Pragma("unroll") for (int k = 0; k < 2; ++k) dst[m][k] = *(const PG8_LAS bf16x8*)(lds + PG8_SA(b, h) + aoff + m * 2048 + k * 1024); } while (0)
; #define PG8_LDB(dst, b, h) do { _Pragma("unroll") for (int n = 0; n < 2; ++n) _Pragma("unroll") for (int k = 0; k < 2; ++k) dst[n][k] = *(const PG8_LAS bf16x8*)(lds + PG8_SB(b, h) + boff + n * 2048 + k * 1024); } while (0)
; #define PG8_MMA(ai, bj, At, Bt) do { __builtin_amdgcn_s_setprio(1); _Pragma("unroll") for (int m = 0; m < 4; ++m) _Pragma("unroll") for (int n = 0; n < 2; ++n) _Pragma("unroll") for (int k = 0; k < 2; ++k) \
;         acc[ai][bj][m][n] = __builtin_amdgcn_mfma_f32_16x16x32_bf16(Bt[n][k], At[m][k], acc[ai][bj][m][n], 0, 0, 0); __builtin_amdgcn_s_setprio(0); } while (0)
; #define PG8_WAIT_V(n) asm volatile("s_waitcnt vmcnt(" #n ")" ::: "memory")
; #define PG8_BAR __builtin_amdgcn_s_barrier()
; template <class Epi, class Sched, bool ALIGN_EPI = false, bool SP2 = false>
; __device__ __forceinline__ void gemm_phase(PG8_LAS unsigned char* lds, const Gemm g, const Sched& S, const Epi& E) {
;     ...
;         for (int t = 0; t < nt; t += 2) {
;             const bool last = (t == nt - 2);
;             const char* a1 = cA + (size_t)(t + 1) * kstep;
;             const char* a2 = last ? nA : cA + (size_t)(t + 2) * kstep; const char* b2 = last ? nB : cB + (size_t)(t + 2) * kstep;
;             const char* a3 = a2 + kstep; const char* b3 = b2 + kstep;
;             if (last && has_next) S.a_ready(nxt);
;             if constexpr (SP2) {
;             PG8_LDB(B0, 0, 0); PG8_LDB(B1, 0, 1); PG8_SCHED; PG8_LDA(At, 0, 0); PG8_STAGE(PG8_SA(1, 1), a1 + hstep, voffA);
;             PG8_WAIT_V(8); PG8_WAIT_L(0); PG8_BAR; PG8_MMA(0, 0, At, B0); PG8_MMA(0, 1, At, B1); PG8_BAR; PG8_SCHED;
;             PG8_LDA(At, 0, 1); PG8_STAGE(PG8_SB(0, 0), b2, voffB); PG8_STAGE(PG8_SB(0, 1), b2 + hstep, voffB); PG8_STAGE(PG8_SA(0, 0), a2, voffA);
;             PG8_WAIT_V(8); PG8_WAIT_L(0); PG8_BAR; PG8_MMA(1, 0, At, B0); PG8_MMA(1, 1, At, B1); PG8_BAR; PG8_SCHED;
.LBB0_55:
	s_add_u32 s28, s42, 0xfff80080
	s_addc_u32 s29, s43, -1
	s_add_i32 s72, 0, 0x10000
	s_cmp_eq_u32 s71, 28
	s_cselect_b32 s53, s27, s29
	s_cselect_b32 s52, s65, s28
	s_cselect_b32 s51, s25, s70
	s_cselect_b32 s50, s66, s67
	s_add_i32 s73, 0, 0x14000
	v_add_u32_e32 v76, s72, v163
	v_add_u32_e32 v160, s73, v163
	ds_read_b128 v[64:67], v76
	ds_read_b128 v[68:71], v76 offset:1024
	ds_read_b128 v[72:75], v76 offset:2048
	ds_read_b128 v[76:79], v76 offset:3072
	ds_read_b128 v[156:159], v160
	ds_read_b128 v[168:171], v160 offset:1024
	ds_read_b128 v[172:175], v160 offset:2048
	ds_read_b128 v[176:179], v160 offset:3072
	v_lshl_add_u64 v[160:161], s[42:43], 0, v[152:153]
	s_add_i32 m0, s12, 0xc000
	ds_read_b128 v[180:183], v165
	ds_read_b128 v[184:187], v165 offset:1024
	ds_read_b128 v[188:191], v165 offset:2048
	ds_read_b128 v[196:199], v165 offset:3072
	ds_read_b128 v[200:203], v165 offset:4096
	ds_read_b128 v[204:207], v165 offset:5120
	ds_read_b128 v[208:211], v165 offset:6144
	ds_read_b128 v[222:225], v165 offset:7168
	global_load_lds_dwordx4 v[160:161], off
	v_lshl_add_u64 v[160:161], s[42:43], 0, v[154:155]
	s_add_i32 m0, s12, 0xe000
	s_nop 0
	global_load_lds_dwordx4 v[160:161], off
	s_waitcnt vmcnt(8)
	s_waitcnt lgkmcnt(0)
	s_barrier
	s_setprio 1
	s_waitcnt lgkmcnt(0)
	v_mfma_f32_16x16x32_bf16 v[140:143], v[64:67], v[180:183], v[140:143]
	v_mfma_f32_16x16x32_bf16 v[136:139], v[72:75], v[180:183], v[136:139]
	v_mfma_f32_16x16x32_bf16 v[124:127], v[64:67], v[188:191], v[124:127]
	v_mfma_f32_16x16x32_bf16 v[120:123], v[72:75], v[188:191], v[120:123]
	v_mfma_f32_16x16x32_bf16 v[108:111], v[64:67], v[200:203], v[108:111]
	v_mfma_f32_16x16x32_bf16 v[104:107], v[72:75], v[200:203], v[104:107]
	v_mfma_f32_16x16x32_bf16 v[92:95], v[64:67], v[208:211], v[92:95]
	v_mfma_f32_16x16x32_bf16 v[88:91], v[72:75], v[208:211], v[88:91]
	v_mfma_f32_16x16x32_bf16 v[140:143], v[68:71], v[184:187], v[140:143]
	v_mfma_f32_16x16x32_bf16 v[136:139], v[76:79], v[184:187], v[136:139]
	v_mfma_f32_16x16x32_bf16 v[124:127], v[68:71], v[196:199], v[124:127]
	v_mfma_f32_16x16x32_bf16 v[120:123], v[76:79], v[196:199], v[120:123]
	v_mfma_f32_16x16x32_bf16 v[108:111], v[68:71], v[204:207], v[108:111]
	v_mfma_f32_16x16x32_bf16 v[104:107], v[76:79], v[204:207], v[104:107]
	v_mfma_f32_16x16x32_bf16 v[92:95], v[68:71], v[222:225], v[92:95]
	v_mfma_f32_16x16x32_bf16 v[88:91], v[76:79], v[222:225], v[88:91]
	v_mfma_f32_16x16x32_bf16 v[132:135], v[156:159], v[180:183], v[132:135]
	v_mfma_f32_16x16x32_bf16 v[128:131], v[172:175], v[180:183], v[128:131]
	v_mfma_f32_16x16x32_bf16 v[116:119], v[156:159], v[188:191], v[116:119]
	v_mfma_f32_16x16x32_bf16 v[112:115], v[172:175], v[188:191], v[112:115]
	v_mfma_f32_16x16x32_bf16 v[100:103], v[156:159], v[200:203], v[100:103]
	v_mfma_f32_16x16x32_bf16 v[96:99], v[172:175], v[200:203], v[96:99]
	v_mfma_f32_16x16x32_bf16 v[84:87], v[156:159], v[208:211], v[84:87]
	v_mfma_f32_16x16x32_bf16 v[80:83], v[172:175], v[208:211], v[80:83]
	v_mfma_f32_16x16x32_bf16 v[132:135], v[168:171], v[184:187], v[132:135]
	v_mfma_f32_16x16x32_bf16 v[128:131], v[176:179], v[184:187], v[128:131]
	v_mfma_f32_16x16x32_bf16 v[116:119], v[168:171], v[196:199], v[116:119]
	v_mfma_f32_16x16x32_bf16 v[112:115], v[176:179], v[196:199], v[112:115]
	v_mfma_f32_16x16x32_bf16 v[100:103], v[168:171], v[204:207], v[100:103]
	v_mfma_f32_16x16x32_bf16 v[96:99], v[176:179], v[204:207], v[96:99]
	v_mfma_f32_16x16x32_bf16 v[84:87], v[168:171], v[222:225], v[84:87]
	v_mfma_f32_16x16x32_bf16 v[80:83], v[176:179], v[222:225], v[80:83]
	s_setprio 0
	s_barrier
	s_add_i32 s28, s72, s8
	v_lshl_add_u64 v[160:161], s[50:51], 0, v[194:195]
	s_mov_b32 m0, s28
	ds_read_b128 v[180:183], v165 offset:16384
	ds_read_b128 v[184:187], v165 offset:17408
	ds_read_b128 v[188:191], v165 offset:18432
	ds_read_b128 v[196:199], v165 offset:19456
	ds_read_b128 v[200:203], v165 offset:20480
	ds_read_b128 v[204:207], v165 offset:21504
	ds_read_b128 v[208:211], v165 offset:22528
	ds_read_b128 v[222:225], v165 offset:23552
	global_load_lds_dwordx4 v[160:161], off
	s_add_i32 m0, s28, 0x2000
	s_add_u32 s28, s50, 0x80000
	v_lshl_add_u64 v[192:193], s[50:51], 0, v[144:145]
	s_addc_u32 s29, s51, 0
	s_add_i32 s72, s73, s8
	global_load_lds_dwordx4 v[192:193], off
	v_lshl_add_u64 v[212:213], s[28:29], 0, v[194:195]
	s_mov_b32 m0, s72
	v_lshl_add_u64 v[228:229], s[52:53], 0, v[146:147]
	global_load_lds_dwordx4 v[212:213], off
	v_lshl_add_u64 v[212:213], s[28:29], 0, v[144:145]
	s_add_i32 m0, s72, 0x2000
	s_nop 0
	global_load_lds_dwordx4 v[212:213], off
	v_lshl_add_u64 v[212:213], s[52:53], 0, v[148:149]
	s_mov_b32 m0, s12
	s_nop 0
	global_load_lds_dwordx4 v[212:213], off
	s_mov_b32 m0, s20
	s_nop 0
	global_load_lds_dwordx4 v[228:229], off
	s_waitcnt vmcnt(8)
	s_waitcnt lgkmcnt(0)
	s_barrier
; #define PG8_STAGE(bufoff, gbase, voff) do { _Pragma("unroll") for (int _i = 0; _i < 2; ++_i) \
;         __builtin_amdgcn_global_load_lds((const unsigned*)((const char*)(gbase) + (voff)[_i]), (PG8_LAS unsigned*)(lds + (bufoff) + ldsw + _i * 8192), 16, 0, 0); } while (0)
; #define PG8_LDA(dst, b, h) do { _Pragma("unroll") for (int m = 0; m < 4; ++m) _Pragma("unroll") for (int k = 0; k < 2; ++k) dst[m][k] = *(const PG8_LAS bf16x8*)(lds + PG8_SA(b, h) + aoff + m * 2048 + k * 1024); } while (0)
; #define PG8_LDB(dst, b, h) do { _Pragma("unroll") for (int n = 0; n < 2; ++n) _Pragma("unroll") for (int k = 0; k < 2; ++k) dst[n][k] = *(const PG8_LAS bf16x8*)(lds + PG8_SB(b, h) + boff + n * 2048 + k * 1024); } while (0)
; #define PG8_MMA(ai, bj, At, Bt) do { __builtin_amdgcn_s_setprio(1); _Pragma("unroll") for (int m = 0; m < 4; ++m) _Pragma("unroll") for (int n = 0; n < 2; ++n) _Pragma("unroll") for (int k = 0; k < 2; ++k) \
;         acc[ai][bj][m][n] = __builtin_amdgcn_mfma_f32_16x16x32_bf16(Bt[n][k], At[m][k], acc[ai][bj][m][n], 0, 0, 0); __builtin_amdgcn_s_setprio(0); } while (0)
; #define PG8_WAIT_V(n) asm volatile("s_waitcnt vmcnt(" #n ")" ::: "memory")
; #define PG8_WAIT_L(n) asm volatile("s_waitcnt lgkmcnt(" #n ")" ::: "memory")
; #define PG8_BAR __builtin_amdgcn_s_barrier()
; #define PG8_SCHED __builtin_amdgcn_sched_barrier(0)
; template <class Epi, class Sched, bool ALIGN_EPI = false, bool SP2 = false>
; __device__ __forceinline__ void gemm_phase(PG8_LAS unsigned char* lds, const Gemm g, const Sched& S, const Epi& E) {
;     ...
;             PG8_WAIT_V(8); PG8_WAIT_L(0); PG8_BAR; PG8_MMA(1, 0, At, B0); PG8_MMA(1, 1, At, B1); PG8_BAR; PG8_SCHED;
;             PG8_LDB(B0, 1, 0); PG8_LDB(B1, 1, 1); PG8_SCHED; PG8_LDA(At, 1, 0); PG8_STAGE(PG8_SA(0, 1), a2 + hstep, voffA);
;             PG8_WAIT_V(8); PG8_WAIT_L(0); PG8_BAR; PG8_MMA(0, 0, At, B0); PG8_MMA(0, 1, At, B1); PG8_BAR; PG8_SCHED;
	s_setprio 1
	s_waitcnt lgkmcnt(0)
	v_mfma_f32_16x16x32_bf16 v[60:63], v[64:67], v[180:183], v[60:63]
	v_mfma_f32_16x16x32_bf16 v[56:59], v[72:75], v[180:183], v[56:59]
	v_mfma_f32_16x16x32_bf16 v[44:47], v[64:67], v[188:191], v[44:47]
	v_mfma_f32_16x16x32_bf16 v[40:43], v[72:75], v[188:191], v[40:43]
	v_mfma_f32_16x16x32_bf16 v[28:31], v[64:67], v[200:203], v[28:31]
	v_mfma_f32_16x16x32_bf16 v[24:27], v[72:75], v[200:203], v[24:27]
	v_mfma_f32_16x16x32_bf16 v[12:15], v[64:67], v[208:211], v[12:15]
	v_mfma_f32_16x16x32_bf16 v[8:11], v[72:75], v[208:211], v[8:11]
	v_mfma_f32_16x16x32_bf16 v[60:63], v[68:71], v[184:187], v[60:63]
	v_mfma_f32_16x16x32_bf16 v[56:59], v[76:79], v[184:187], v[56:59]
	v_mfma_f32_16x16x32_bf16 v[44:47], v[68:71], v[196:199], v[44:47]
	v_mfma_f32_16x16x32_bf16 v[40:43], v[76:79], v[196:199], v[40:43]
	v_mfma_f32_16x16x32_bf16 v[28:31], v[68:71], v[204:207], v[28:31]
	v_mfma_f32_16x16x32_bf16 v[24:27], v[76:79], v[204:207], v[24:27]
	v_mfma_f32_16x16x32_bf16 v[12:15], v[68:71], v[222:225], v[12:15]
	v_mfma_f32_16x16x32_bf16 v[8:11], v[76:79], v[222:225], v[8:11]
	v_mfma_f32_16x16x32_bf16 v[52:55], v[156:159], v[180:183], v[52:55]
	v_mfma_f32_16x16x32_bf16 v[48:51], v[172:175], v[180:183], v[48:51]
	v_mfma_f32_16x16x32_bf16 v[36:39], v[156:159], v[188:191], v[36:39]
	v_mfma_f32_16x16x32_bf16 v[32:35], v[172:175], v[188:191], v[32:35]
	v_mfma_f32_16x16x32_bf16 v[20:23], v[156:159], v[200:203], v[20:23]
	v_mfma_f32_16x16x32_bf16 v[16:19], v[172:175], v[200:203], v[16:19]
	v_mfma_f32_16x16x32_bf16 v[4:7], v[156:159], v[208:211], v[4:7]
	v_mfma_f32_16x16x32_bf16 v[0:3], v[172:175], v[208:211], v[0:3]
	v_mfma_f32_16x16x32_bf16 v[52:55], v[168:171], v[184:187], v[52:55]
	v_mfma_f32_16x16x32_bf16 v[48:51], v[176:179], v[184:187], v[48:51]
	v_mfma_f32_16x16x32_bf16 v[36:39], v[168:171], v[196:199], v[36:39]
	v_mfma_f32_16x16x32_bf16 v[32:35], v[176:179], v[196:199], v[32:35]
	v_mfma_f32_16x16x32_bf16 v[20:23], v[168:171], v[204:207], v[20:23]
	v_mfma_f32_16x16x32_bf16 v[16:19], v[176:179], v[204:207], v[16:19]
	v_mfma_f32_16x16x32_bf16 v[4:7], v[168:171], v[222:225], v[4:7]
	v_mfma_f32_16x16x32_bf16 v[0:3], v[176:179], v[222:225], v[0:3]
	s_setprio 0
	s_barrier
	s_add_i32 s72, 0, 0x18000
	s_add_i32 s73, 0, 0x1c000
	v_add_u32_e32 v76, s72, v163
	v_add_u32_e32 v167, s73, v163
	ds_read_b128 v[64:67], v76
	ds_read_b128 v[68:71], v76 offset:1024
	ds_read_b128 v[72:75], v76 offset:2048
	ds_read_b128 v[76:79], v76 offset:3072
	ds_read_b128 v[156:159], v167
	ds_read_b128 v[168:171], v167 offset:1024
	ds_read_b128 v[172:175], v167 offset:2048
	ds_read_b128 v[176:179], v167 offset:3072
	s_add_u32 s28, s52, 0x80000
	s_addc_u32 s29, s53, 0
	s_mov_b32 m0, s21
	v_lshl_add_u64 v[230:231], s[28:29], 0, v[148:149]
	ds_read_b128 v[180:183], v165 offset:32768
	ds_read_b128 v[184:187], v165 offset:33792
	ds_read_b128 v[188:191], v165 offset:34816
	ds_read_b128 v[196:199], v165 offset:35840
	ds_read_b128 v[200:203], v165 offset:36864
	ds_read_b128 v[204:207], v165 offset:37888
	ds_read_b128 v[208:211], v165 offset:38912
	ds_read_b128 v[222:225], v165 offset:39936
	global_load_lds_dwordx4 v[230:231], off
	v_lshl_add_u64 v[230:231], s[28:29], 0, v[146:147]
	s_mov_b32 m0, s48
	s_nop 0
	global_load_lds_dwordx4 v[230:231], off
	s_waitcnt vmcnt(8)
	s_waitcnt lgkmcnt(0)
	s_barrier
	s_setprio 1
	s_waitcnt lgkmcnt(0)
	v_mfma_f32_16x16x32_bf16 v[140:143], v[64:67], v[180:183], v[140:143]
	v_mfma_f32_16x16x32_bf16 v[136:139], v[72:75], v[180:183], v[136:139]
	v_mfma_f32_16x16x32_bf16 v[124:127], v[64:67], v[188:191], v[124:127]
	v_mfma_f32_16x16x32_bf16 v[120:123], v[72:75], v[188:191], v[120:123]
	v_mfma_f32_16x16x32_bf16 v[108:111], v[64:67], v[200:203], v[108:111]
	v_mfma_f32_16x16x32_bf16 v[104:107], v[72:75], v[200:203], v[104:107]
	v_mfma_f32_16x16x32_bf16 v[92:95], v[64:67], v[208:211], v[92:95]
	v_mfma_f32_16x16x32_bf16 v[88:91], v[72:75], v[208:211], v[88:91]
	v_mfma_f32_16x16x32_bf16 v[140:143], v[68:71], v[184:187], v[140:143]
	v_mfma_f32_16x16x32_bf16 v[136:139], v[76:79], v[184:187], v[136:139]
	v_mfma_f32_16x16x32_bf16 v[124:127], v[68:71], v[196:199], v[124:127]
	v_mfma_f32_16x16x32_bf16 v[120:123], v[76:79], v[196:199], v[120:123]
	v_mfma_f32_16x16x32_bf16 v[108:111], v[68:71], v[204:207], v[108:111]
	v_mfma_f32_16x16x32_bf16 v[104:107], v[76:79], v[204:207], v[104:107]
	v_mfma_f32_16x16x32_bf16 v[92:95], v[68:71], v[222:225], v[92:95]
	v_mfma_f32_16x16x32_bf16 v[88:91], v[76:79], v[222:225], v[88:91]
	v_mfma_f32_16x16x32_bf16 v[132:135], v[156:159], v[180:183], v[132:135]
	v_mfma_f32_16x16x32_bf16 v[128:131], v[172:175], v[180:183], v[128:131]
	v_mfma_f32_16x16x32_bf16 v[116:119], v[156:159], v[188:191], v[116:119]
	v_mfma_f32_16x16x32_bf16 v[112:115], v[172:175], v[188:191], v[112:115]
	v_mfma_f32_16x16x32_bf16 v[100:103], v[156:159], v[200:203], v[100:103]
	v_mfma_f32_16x16x32_bf16 v[96:99], v[172:175], v[200:203], v[96:99]
	v_mfma_f32_16x16x32_bf16 v[84:87], v[156:159], v[208:211], v[84:87]
	v_mfma_f32_16x16x32_bf16 v[80:83], v[172:175], v[208:211], v[80:83]
	v_mfma_f32_16x16x32_bf16 v[132:135], v[168:171], v[184:187], v[132:135]
	v_mfma_f32_16x16x32_bf16 v[128:131], v[176:179], v[184:187], v[128:131]
	v_mfma_f32_16x16x32_bf16 v[116:119], v[168:171], v[196:199], v[116:119]
	v_mfma_f32_16x16x32_bf16 v[112:115], v[176:179], v[196:199], v[112:115]
	v_mfma_f32_16x16x32_bf16 v[100:103], v[168:171], v[204:207], v[100:103]
	v_mfma_f32_16x16x32_bf16 v[96:99], v[176:179], v[204:207], v[96:99]
	v_mfma_f32_16x16x32_bf16 v[84:87], v[168:171], v[222:225], v[84:87]
	v_mfma_f32_16x16x32_bf16 v[80:83], v[176:179], v[222:225], v[80:83]
	s_setprio 0
	s_barrier
; #define PG8_STAGE(bufoff, gbase, voff) do { _Pragma("unroll") for (int _i = 0; _i < 2; ++_i) \
;         __builtin_amdgcn_global_load_lds((const unsigned*)((const char*)(gbase) + (voff)[_i]), (PG8_LAS unsigned*)(lds + (bufoff) + ldsw + _i * 8192), 16, 0, 0); } while (0)
; #define PG8_LDA(dst, b, h) do { _Pragma("unroll") for (int m = 0; m < 4; ++m) _Pragma("unroll") for (int k = 0; k < 2; ++k) dst[m][k] = *(const PG8_LAS bf16x8*)(lds + PG8_SA(b, h) + aoff + m * 2048 + k * 1024); } while (0)
; #define PG8_MMA(ai, bj, At, Bt) do { __builtin_amdgcn_s_setprio(1); _Pragma("unroll") for (int m = 0; m < 4; ++m) _Pragma("unroll") for (int n = 0; n < 2; ++n) _Pragma("unroll") for (int k = 0; k < 2; ++k) \
;         acc[ai][bj][m][n] = __builtin_amdgcn_mfma_f32_16x16x32_bf16(Bt[n][k], At[m][k], acc[ai][bj][m][n], 0, 0, 0); __builtin_amdgcn_s_setprio(0); } while (0)
; #define PG8_WAIT_V(n) asm volatile("s_waitcnt vmcnt(" #n ")" ::: "memory")
; #define PG8_WAIT_L(n) asm volatile("s_waitcnt lgkmcnt(" #n ")" ::: "memory")
; #define PG8_BAR __builtin_amdgcn_s_barrier()
; #define PG8_SCHED __builtin_amdgcn_sched_barrier(0)
; template <class Epi, class Sched, bool ALIGN_EPI = false, bool SP2 = false>
; __device__ __forceinline__ void gemm_phase(PG8_LAS unsigned char* lds, const Gemm g, const Sched& S, const Epi& E) {
;     ...
;             PG8_LDA(At, 1, 1); PG8_STAGE(PG8_SB(1, 0), b3, voffB); PG8_STAGE(PG8_SB(1, 1), b3 + hstep, voffB); PG8_STAGE(PG8_SA(1, 0), a3, voffA);
;             PG8_WAIT_V(8); PG8_WAIT_L(0); PG8_BAR; PG8_MMA(1, 0, At, B0); PG8_MMA(1, 1, At, B1); PG8_BAR; PG8_SCHED;
;     ...
;         }
;         if constexpr (ALIGN_EPI) { if (wr == 0) PG8_BAR; }
	s_add_i32 s28, s72, s8
	v_lshl_add_u64 v[160:161], v[160:161], 0, s[30:31]
	s_mov_b32 m0, s28
	ds_read_b128 v[180:183], v165 offset:49152
	ds_read_b128 v[184:187], v165 offset:50176
	ds_read_b128 v[188:191], v165 offset:51200
	ds_read_b128 v[196:199], v165 offset:52224
	ds_read_b128 v[200:203], v165 offset:53248
	ds_read_b128 v[204:207], v165 offset:54272
	ds_read_b128 v[208:211], v165 offset:55296
	ds_read_b128 v[222:225], v165 offset:56320
	global_load_lds_dwordx4 v[160:161], off
	s_add_i32 m0, s28, 0x2000
	s_add_u32 s28, s50, 0x80080
	v_lshl_add_u64 v[160:161], v[192:193], 0, s[30:31]
	s_addc_u32 s29, s51, 0
	s_add_i32 s50, s73, s8
	global_load_lds_dwordx4 v[160:161], off
	v_lshl_add_u64 v[160:161], s[28:29], 0, v[194:195]
	s_mov_b32 m0, s50
	s_nop 0
	global_load_lds_dwordx4 v[160:161], off
	v_lshl_add_u64 v[160:161], s[28:29], 0, v[144:145]
	s_add_i32 m0, s50, 0x2000
	s_nop 0
	global_load_lds_dwordx4 v[160:161], off
	v_lshl_add_u64 v[160:161], v[212:213], 0, s[30:31]
	s_mov_b32 m0, s55
	s_nop 0
	global_load_lds_dwordx4 v[160:161], off
	v_lshl_add_u64 v[160:161], v[228:229], 0, s[30:31]
	s_mov_b32 m0, s60
	s_nop 0
	global_load_lds_dwordx4 v[160:161], off
	s_waitcnt vmcnt(8)
	s_waitcnt lgkmcnt(0)
	s_barrier
	s_setprio 1
	s_waitcnt lgkmcnt(0)
	v_mfma_f32_16x16x32_bf16 v[60:63], v[64:67], v[180:183], v[60:63]
	v_mfma_f32_16x16x32_bf16 v[56:59], v[72:75], v[180:183], v[56:59]
	v_mfma_f32_16x16x32_bf16 v[44:47], v[64:67], v[188:191], v[44:47]
	v_mfma_f32_16x16x32_bf16 v[40:43], v[72:75], v[188:191], v[40:43]
	v_mfma_f32_16x16x32_bf16 v[28:31], v[64:67], v[200:203], v[28:31]
	v_mfma_f32_16x16x32_bf16 v[24:27], v[72:75], v[200:203], v[24:27]
	v_mfma_f32_16x16x32_bf16 v[12:15], v[64:67], v[208:211], v[12:15]
	v_mfma_f32_16x16x32_bf16 v[8:11], v[72:75], v[208:211], v[8:11]
	v_mfma_f32_16x16x32_bf16 v[60:63], v[68:71], v[184:187], v[60:63]
	v_mfma_f32_16x16x32_bf16 v[56:59], v[76:79], v[184:187], v[56:59]
	v_mfma_f32_16x16x32_bf16 v[44:47], v[68:71], v[196:199], v[44:47]
	v_mfma_f32_16x16x32_bf16 v[40:43], v[76:79], v[196:199], v[40:43]
	v_mfma_f32_16x16x32_bf16 v[28:31], v[68:71], v[204:207], v[28:31]
	v_mfma_f32_16x16x32_bf16 v[24:27], v[76:79], v[204:207], v[24:27]
	v_mfma_f32_16x16x32_bf16 v[12:15], v[68:71], v[222:225], v[12:15]
	v_mfma_f32_16x16x32_bf16 v[8:11], v[76:79], v[222:225], v[8:11]
	v_mfma_f32_16x16x32_bf16 v[52:55], v[156:159], v[180:183], v[52:55]
	v_mfma_f32_16x16x32_bf16 v[48:51], v[172:175], v[180:183], v[48:51]
	v_mfma_f32_16x16x32_bf16 v[36:39], v[156:159], v[188:191], v[36:39]
	v_mfma_f32_16x16x32_bf16 v[32:35], v[172:175], v[188:191], v[32:35]
	v_mfma_f32_16x16x32_bf16 v[20:23], v[156:159], v[200:203], v[20:23]
	v_mfma_f32_16x16x32_bf16 v[16:19], v[172:175], v[200:203], v[16:19]
	v_mfma_f32_16x16x32_bf16 v[4:7], v[156:159], v[208:211], v[4:7]
	v_mfma_f32_16x16x32_bf16 v[0:3], v[172:175], v[208:211], v[0:3]
	v_mfma_f32_16x16x32_bf16 v[52:55], v[168:171], v[184:187], v[52:55]
	v_mfma_f32_16x16x32_bf16 v[48:51], v[176:179], v[184:187], v[48:51]
	v_mfma_f32_16x16x32_bf16 v[36:39], v[168:171], v[196:199], v[36:39]
	v_mfma_f32_16x16x32_bf16 v[32:35], v[176:179], v[196:199], v[32:35]
	v_mfma_f32_16x16x32_bf16 v[20:23], v[168:171], v[204:207], v[20:23]
	v_mfma_f32_16x16x32_bf16 v[16:19], v[176:179], v[204:207], v[16:19]
	v_mfma_f32_16x16x32_bf16 v[4:7], v[168:171], v[222:225], v[4:7]
	v_mfma_f32_16x16x32_bf16 v[0:3], v[176:179], v[222:225], v[0:3]
	s_setprio 0
	s_barrier
	s_add_i32 s71, s71, 2
	s_add_u32 s42, s42, 0x100
	s_addc_u32 s43, s43, 0
	s_add_u32 s67, s67, 0x100
	s_addc_u32 s70, s70, 0
	s_cmp_gt_u32 s71, 29
	s_cbranch_scc0 .LBB0_55
	s_and_b64 vcc, exec, s[22:23]
	s_cbranch_vccz .LBB0_58
	s_barrier

; #define PG8_STAGE(bufoff, gbase, voff) do { _Pragma("unroll") for (int _i = 0; _i < 2; ++_i) \
;         __builtin_amdgcn_global_load_lds((const unsigned*)((const char*)(gbase) + (voff)[_i]), (PG8_LAS unsigned*)(lds + (bufoff) + ldsw + _i * 8192), 16, 0, 0); } while (0)
; #define PG8_LDA(dst, b, h) do { _Pragma("unroll") for (int m = 0; m < 4; ++m) _Pragma("unroll") for (int k = 0; k < 2; ++k) dst[m][k] = *(const PG8_LAS bf16x8*)(lds + PG8_SA(b, h) + aoff + m * 2048 + k * 1024); } while (0)
; #define PG8_LDB(dst, b, h) do { _Pragma("unroll") for (int n = 0; n < 2; ++n) _Pragma("unroll") for (int k = 0; k < 2; ++k) dst[n][k] = *(const PG8_LAS bf16x8*)(lds + PG8_SB(b, h) + boff + n * 2048 + k * 1024); } while (0)
; #define PG8_MMA(ai, bj, At, Bt) do { __builtin_amdgcn_s_setprio(1); _Pragma("unroll") for (int m = 0; m < 4; ++m) _Pragma("unroll") for (int n = 0; n < 2; ++n) _Pragma("unroll") for (int k = 0; k < 2; ++k) \
;         acc[ai][bj][m][n] = __builtin_amdgcn_mfma_f32_16x16x32_bf16(Bt[n][k], At[m][k], acc[ai][bj][m][n], 0, 0, 0); __builtin_amdgcn_s_setprio(0); } while (0)
; #define PG8_WAIT_V(n) asm volatile("s_waitcnt vmcnt(" #n ")" ::: "memory")
; #define PG8_BAR __builtin_amdgcn_s_barrier()
; template <class Epi, class Sched, bool ALIGN_EPI = false, bool SP2 = false>
; __device__ __forceinline__ void gemm_phase(PG8_LAS unsigned char* lds, const Gemm g, const Sched& S, const Epi& E) {
;     ...
;         for (int t = 0; t < nt; t += 2) {
;             const bool last = (t == nt - 2);
;             const char* a1 = cA + (size_t)(t + 1) * kstep;
;             const char* a2 = last ? nA : cA + (size_t)(t + 2) * kstep; const char* b2 = last ? nB : cB + (size_t)(t + 2) * kstep;
;             const char* a3 = a2 + kstep; const char* b3 = b2 + kstep;
;             if (last && has_next) S.a_ready(nxt);
;             if constexpr (SP2) {
;             PG8_LDB(B0, 0, 0); PG8_LDB(B1, 0, 1); PG8_SCHED; PG8_LDA(At, 0, 0); PG8_STAGE(PG8_SA(1, 1), a1 + hstep, voffA);
;             PG8_WAIT_V(8); PG8_WAIT_L(0); PG8_BAR; PG8_MMA(0, 0, At, B0); PG8_MMA(0, 1, At, B1); PG8_BAR; PG8_SCHED;
;             PG8_LDA(At, 0, 1); PG8_STAGE(PG8_SB(0, 0), b2, voffB); PG8_STAGE(PG8_SB(0, 1), b2 + hstep, voffB); PG8_STAGE(PG8_SA(0, 0), a2, voffA);
;             PG8_WAIT_V(8); PG8_WAIT_L(0); PG8_BAR; PG8_MMA(1, 0, At, B0); PG8_MMA(1, 1, At, B1); PG8_BAR; PG8_SCHED;
.LBB0_82:
	s_add_i32 s28, s46, 2
	s_add_u32 s29, s44, 0x80
	s_addc_u32 s47, s45, 0
	s_add_i32 s12, 0, 0x10000
	s_cmp_eq_u32 s24, s46
	s_cselect_b32 s47, s65, s47
	s_cselect_b32 s46, s92, s29
	s_cselect_b32 s73, s61, vcc_hi
	s_cselect_b32 s72, s93, vcc_lo
	s_add_i32 s29, 0, 0x14000
	v_add_u32_e32 v68, s12, v235
	v_add_u32_e32 v156, s29, v235
	ds_read_b128 v[56:59], v68
	ds_read_b128 v[60:63], v68 offset:1024
	ds_read_b128 v[64:67], v68 offset:2048
	ds_read_b128 v[68:71], v68 offset:3072
	ds_read_b128 v[144:147], v156
	ds_read_b128 v[148:151], v156 offset:1024
	ds_read_b128 v[152:155], v156 offset:2048
	ds_read_b128 v[156:159], v156 offset:3072
	v_lshl_add_u64 v[204:205], s[44:45], 0, v[182:183]
	s_add_i32 m0, s70, 0xc000
	ds_read_b128 v[160:163], v237
	ds_read_b128 v[164:167], v237 offset:1024
	ds_read_b128 v[168:171], v237 offset:2048
	ds_read_b128 v[172:175], v237 offset:3072
	ds_read_b128 v[186:189], v237 offset:4096
	ds_read_b128 v[190:193], v237 offset:5120
	ds_read_b128 v[196:199], v237 offset:6144
	ds_read_b128 v[200:203], v237 offset:7168
	global_load_lds_dwordx4 v[204:205], off
	v_lshl_add_u64 v[204:205], s[44:45], 0, v[184:185]
	s_add_i32 m0, s70, 0xe000
	s_nop 0
	global_load_lds_dwordx4 v[204:205], off
	s_waitcnt vmcnt(8)
	s_waitcnt lgkmcnt(0)
	s_barrier
	s_setprio 1
	s_waitcnt lgkmcnt(0)
	v_mfma_f32_16x16x32_bf16 v[140:143], v[56:59], v[160:163], v[140:143]
	v_mfma_f32_16x16x32_bf16 v[136:139], v[64:67], v[160:163], v[136:139]
	v_mfma_f32_16x16x32_bf16 v[124:127], v[56:59], v[168:171], v[124:127]
	v_mfma_f32_16x16x32_bf16 v[120:123], v[64:67], v[168:171], v[120:123]
	v_mfma_f32_16x16x32_bf16 v[108:111], v[56:59], v[186:189], v[108:111]
	v_mfma_f32_16x16x32_bf16 v[104:107], v[64:67], v[186:189], v[104:107]
	v_mfma_f32_16x16x32_bf16 v[92:95], v[56:59], v[196:199], v[92:95]
	v_mfma_f32_16x16x32_bf16 v[88:91], v[64:67], v[196:199], v[88:91]
	v_mfma_f32_16x16x32_bf16 v[140:143], v[60:63], v[164:167], v[140:143]
	v_mfma_f32_16x16x32_bf16 v[136:139], v[68:71], v[164:167], v[136:139]
	v_mfma_f32_16x16x32_bf16 v[124:127], v[60:63], v[172:175], v[124:127]
	v_mfma_f32_16x16x32_bf16 v[120:123], v[68:71], v[172:175], v[120:123]
	v_mfma_f32_16x16x32_bf16 v[108:111], v[60:63], v[190:193], v[108:111]
	v_mfma_f32_16x16x32_bf16 v[104:107], v[68:71], v[190:193], v[104:107]
	v_mfma_f32_16x16x32_bf16 v[92:95], v[60:63], v[200:203], v[92:95]
	v_mfma_f32_16x16x32_bf16 v[88:91], v[68:71], v[200:203], v[88:91]
	v_mfma_f32_16x16x32_bf16 v[132:135], v[144:147], v[160:163], v[132:135]
	v_mfma_f32_16x16x32_bf16 v[128:131], v[152:155], v[160:163], v[128:131]
	v_mfma_f32_16x16x32_bf16 v[116:119], v[144:147], v[168:171], v[116:119]
	v_mfma_f32_16x16x32_bf16 v[112:115], v[152:155], v[168:171], v[112:115]
	v_mfma_f32_16x16x32_bf16 v[100:103], v[144:147], v[186:189], v[100:103]
	v_mfma_f32_16x16x32_bf16 v[96:99], v[152:155], v[186:189], v[96:99]
	v_mfma_f32_16x16x32_bf16 v[84:87], v[144:147], v[196:199], v[84:87]
	v_mfma_f32_16x16x32_bf16 v[80:83], v[152:155], v[196:199], v[80:83]
	v_mfma_f32_16x16x32_bf16 v[132:135], v[148:151], v[164:167], v[132:135]
	v_mfma_f32_16x16x32_bf16 v[128:131], v[156:159], v[164:167], v[128:131]
	v_mfma_f32_16x16x32_bf16 v[116:119], v[148:151], v[172:175], v[116:119]
	v_mfma_f32_16x16x32_bf16 v[112:115], v[156:159], v[172:175], v[112:115]
	v_mfma_f32_16x16x32_bf16 v[100:103], v[148:151], v[190:193], v[100:103]
	v_mfma_f32_16x16x32_bf16 v[96:99], v[156:159], v[190:193], v[96:99]
	v_mfma_f32_16x16x32_bf16 v[84:87], v[148:151], v[200:203], v[84:87]
	v_mfma_f32_16x16x32_bf16 v[80:83], v[156:159], v[200:203], v[80:83]
	s_setprio 0
	s_barrier
	s_add_i32 s12, s12, s2
	v_lshl_add_u64 v[204:205], s[72:73], 0, v[194:195]
	s_mov_b32 m0, s12
	ds_read_b128 v[160:163], v237 offset:16384
	ds_read_b128 v[164:167], v237 offset:17408
	ds_read_b128 v[168:171], v237 offset:18432
	ds_read_b128 v[172:175], v237 offset:19456
	ds_read_b128 v[186:189], v237 offset:20480
	ds_read_b128 v[190:193], v237 offset:21504
	ds_read_b128 v[196:199], v237 offset:22528
	ds_read_b128 v[200:203], v237 offset:23552
	global_load_lds_dwordx4 v[204:205], off
	s_add_i32 m0, s12, 0x2000
	v_lshl_add_u64 v[206:207], s[72:73], 0, v[176:177]
	s_add_u32 s72, s72, s22
	s_addc_u32 s73, s73, 0
	s_add_i32 s12, s29, s2
	global_load_lds_dwordx4 v[206:207], off
	v_lshl_add_u64 v[208:209], s[72:73], 0, v[194:195]
	s_mov_b32 m0, s12
	v_lshl_add_u64 v[210:211], s[72:73], 0, v[176:177]
	global_load_lds_dwordx4 v[208:209], off
	s_add_i32 m0, s12, 0x2000
	v_lshl_add_u64 v[212:213], s[46:47], 0, v[180:181]
	global_load_lds_dwordx4 v[210:211], off
	s_mov_b32 m0, s70
	v_lshl_add_u64 v[222:223], s[46:47], 0, v[178:179]
	global_load_lds_dwordx4 v[212:213], off
	s_mov_b32 m0, s71
	s_nop 0
	global_load_lds_dwordx4 v[222:223], off
	s_waitcnt vmcnt(8)
	s_waitcnt lgkmcnt(0)
	s_barrier
; #define PG8_STAGE(bufoff, gbase, voff) do { _Pragma("unroll") for (int _i = 0; _i < 2; ++_i) \
;         __builtin_amdgcn_global_load_lds((const unsigned*)((const char*)(gbase) + (voff)[_i]), (PG8_LAS unsigned*)(lds + (bufoff) + ldsw + _i * 8192), 16, 0, 0); } while (0)
; #define PG8_LDA(dst, b, h) do { _Pragma("unroll") for (int m = 0; m < 4; ++m) _Pragma("unroll") for (int k = 0; k < 2; ++k) dst[m][k] = *(const PG8_LAS bf16x8*)(lds + PG8_SA(b, h) + aoff + m * 2048 + k * 1024); } while (0)
; #define PG8_LDB(dst, b, h) do { _Pragma("unroll") for (int n = 0; n < 2; ++n) _Pragma("unroll") for (int k = 0; k < 2; ++k) dst[n][k] = *(const PG8_LAS bf16x8*)(lds + PG8_SB(b, h) + boff + n * 2048 + k * 1024); } while (0)
; #define PG8_MMA(ai, bj, At, Bt) do { __builtin_amdgcn_s_setprio(1); _Pragma("unroll") for (int m = 0; m < 4; ++m) _Pragma("unroll") for (int n = 0; n < 2; ++n) _Pragma("unroll") for (int k = 0; k < 2; ++k) \
;         acc[ai][bj][m][n] = __builtin_amdgcn_mfma_f32_16x16x32_bf16(Bt[n][k], At[m][k], acc[ai][bj][m][n], 0, 0, 0); __builtin_amdgcn_s_setprio(0); } while (0)
; #define PG8_WAIT_V(n) asm volatile("s_waitcnt vmcnt(" #n ")" ::: "memory")
; #define PG8_WAIT_L(n) asm volatile("s_waitcnt lgkmcnt(" #n ")" ::: "memory")
; #define PG8_BAR __builtin_amdgcn_s_barrier()
; #define PG8_SCHED __builtin_amdgcn_sched_barrier(0)
; template <class Epi, class Sched, bool ALIGN_EPI = false, bool SP2 = false>
; __device__ __forceinline__ void gemm_phase(PG8_LAS unsigned char* lds, const Gemm g, const Sched& S, const Epi& E) {
;     ...
;             PG8_WAIT_V(8); PG8_WAIT_L(0); PG8_BAR; PG8_MMA(1, 0, At, B0); PG8_MMA(1, 1, At, B1); PG8_BAR; PG8_SCHED;
;             PG8_LDB(B0, 1, 0); PG8_LDB(B1, 1, 1); PG8_SCHED; PG8_LDA(At, 1, 0); PG8_STAGE(PG8_SA(0, 1), a2 + hstep, voffA);
;             PG8_WAIT_V(8); PG8_WAIT_L(0); PG8_BAR; PG8_MMA(0, 0, At, B0); PG8_MMA(0, 1, At, B1); PG8_BAR; PG8_SCHED;
	s_setprio 1
	s_waitcnt lgkmcnt(0)
	v_mfma_f32_16x16x32_bf16 v[76:79], v[56:59], v[160:163], v[76:79]
	v_mfma_f32_16x16x32_bf16 v[72:75], v[64:67], v[160:163], v[72:75]
	v_mfma_f32_16x16x32_bf16 v[44:47], v[56:59], v[168:171], v[44:47]
	v_mfma_f32_16x16x32_bf16 v[40:43], v[64:67], v[168:171], v[40:43]
	v_mfma_f32_16x16x32_bf16 v[28:31], v[56:59], v[186:189], v[28:31]
	v_mfma_f32_16x16x32_bf16 v[24:27], v[64:67], v[186:189], v[24:27]
	v_mfma_f32_16x16x32_bf16 v[12:15], v[56:59], v[196:199], v[12:15]
	v_mfma_f32_16x16x32_bf16 v[8:11], v[64:67], v[196:199], v[8:11]
	v_mfma_f32_16x16x32_bf16 v[76:79], v[60:63], v[164:167], v[76:79]
	v_mfma_f32_16x16x32_bf16 v[72:75], v[68:71], v[164:167], v[72:75]
	v_mfma_f32_16x16x32_bf16 v[44:47], v[60:63], v[172:175], v[44:47]
	v_mfma_f32_16x16x32_bf16 v[40:43], v[68:71], v[172:175], v[40:43]
	v_mfma_f32_16x16x32_bf16 v[28:31], v[60:63], v[190:193], v[28:31]
	v_mfma_f32_16x16x32_bf16 v[24:27], v[68:71], v[190:193], v[24:27]
	v_mfma_f32_16x16x32_bf16 v[12:15], v[60:63], v[200:203], v[12:15]
	v_mfma_f32_16x16x32_bf16 v[8:11], v[68:71], v[200:203], v[8:11]
	v_mfma_f32_16x16x32_bf16 v[52:55], v[144:147], v[160:163], v[52:55]
	v_mfma_f32_16x16x32_bf16 v[48:51], v[152:155], v[160:163], v[48:51]
	v_mfma_f32_16x16x32_bf16 v[36:39], v[144:147], v[168:171], v[36:39]
	v_mfma_f32_16x16x32_bf16 v[32:35], v[152:155], v[168:171], v[32:35]
	v_mfma_f32_16x16x32_bf16 v[20:23], v[144:147], v[186:189], v[20:23]
	v_mfma_f32_16x16x32_bf16 v[16:19], v[152:155], v[186:189], v[16:19]
	v_mfma_f32_16x16x32_bf16 v[4:7], v[144:147], v[196:199], v[4:7]
	v_mfma_f32_16x16x32_bf16 v[0:3], v[152:155], v[196:199], v[0:3]
	v_mfma_f32_16x16x32_bf16 v[52:55], v[148:151], v[164:167], v[52:55]
	v_mfma_f32_16x16x32_bf16 v[48:51], v[156:159], v[164:167], v[48:51]
	v_mfma_f32_16x16x32_bf16 v[36:39], v[148:151], v[172:175], v[36:39]
	v_mfma_f32_16x16x32_bf16 v[32:35], v[156:159], v[172:175], v[32:35]
	v_mfma_f32_16x16x32_bf16 v[20:23], v[148:151], v[190:193], v[20:23]
	v_mfma_f32_16x16x32_bf16 v[16:19], v[156:159], v[190:193], v[16:19]
	v_mfma_f32_16x16x32_bf16 v[4:7], v[148:151], v[200:203], v[4:7]
	v_mfma_f32_16x16x32_bf16 v[0:3], v[156:159], v[200:203], v[0:3]
	s_setprio 0
	s_barrier
	s_add_i32 s12, 0, 0x18000
	s_add_i32 s29, 0, 0x1c000
	v_add_u32_e32 v68, s12, v235
	v_add_u32_e32 v156, s29, v235
	ds_read_b128 v[56:59], v68
	ds_read_b128 v[60:63], v68 offset:1024
	ds_read_b128 v[64:67], v68 offset:2048
	ds_read_b128 v[68:71], v68 offset:3072
	ds_read_b128 v[144:147], v156
	ds_read_b128 v[148:151], v156 offset:1024
	ds_read_b128 v[152:155], v156 offset:2048
	ds_read_b128 v[156:159], v156 offset:3072
	s_add_u32 s46, s46, s22
	s_addc_u32 s47, s47, 0
	s_mov_b32 m0, s76
	v_lshl_add_u64 v[224:225], s[46:47], 0, v[180:181]
	ds_read_b128 v[160:163], v237 offset:32768
	ds_read_b128 v[164:167], v237 offset:33792
	ds_read_b128 v[168:171], v237 offset:34816
	ds_read_b128 v[172:175], v237 offset:35840
	ds_read_b128 v[186:189], v237 offset:36864
	ds_read_b128 v[190:193], v237 offset:37888
	ds_read_b128 v[196:199], v237 offset:38912
	ds_read_b128 v[200:203], v237 offset:39936
	global_load_lds_dwordx4 v[224:225], off
	v_lshl_add_u64 v[224:225], s[46:47], 0, v[178:179]
	s_mov_b32 m0, s77
	s_nop 0
	global_load_lds_dwordx4 v[224:225], off
	s_waitcnt vmcnt(8)
	s_waitcnt lgkmcnt(0)
	s_barrier
	s_setprio 1
	s_waitcnt lgkmcnt(0)
	v_mfma_f32_16x16x32_bf16 v[140:143], v[56:59], v[160:163], v[140:143]
	v_mfma_f32_16x16x32_bf16 v[136:139], v[64:67], v[160:163], v[136:139]
	v_mfma_f32_16x16x32_bf16 v[124:127], v[56:59], v[168:171], v[124:127]
	v_mfma_f32_16x16x32_bf16 v[120:123], v[64:67], v[168:171], v[120:123]
	v_mfma_f32_16x16x32_bf16 v[108:111], v[56:59], v[186:189], v[108:111]
	v_mfma_f32_16x16x32_bf16 v[104:107], v[64:67], v[186:189], v[104:107]
	v_mfma_f32_16x16x32_bf16 v[92:95], v[56:59], v[196:199], v[92:95]
	v_mfma_f32_16x16x32_bf16 v[88:91], v[64:67], v[196:199], v[88:91]
	v_mfma_f32_16x16x32_bf16 v[140:143], v[60:63], v[164:167], v[140:143]
	v_mfma_f32_16x16x32_bf16 v[136:139], v[68:71], v[164:167], v[136:139]
	v_mfma_f32_16x16x32_bf16 v[124:127], v[60:63], v[172:175], v[124:127]
	v_mfma_f32_16x16x32_bf16 v[120:123], v[68:71], v[172:175], v[120:123]
	v_mfma_f32_16x16x32_bf16 v[108:111], v[60:63], v[190:193], v[108:111]
	v_mfma_f32_16x16x32_bf16 v[104:107], v[68:71], v[190:193], v[104:107]
	v_mfma_f32_16x16x32_bf16 v[92:95], v[60:63], v[200:203], v[92:95]
	v_mfma_f32_16x16x32_bf16 v[88:91], v[68:71], v[200:203], v[88:91]
	v_mfma_f32_16x16x32_bf16 v[132:135], v[144:147], v[160:163], v[132:135]
	v_mfma_f32_16x16x32_bf16 v[128:131], v[152:155], v[160:163], v[128:131]
	v_mfma_f32_16x16x32_bf16 v[116:119], v[144:147], v[168:171], v[116:119]
	v_mfma_f32_16x16x32_bf16 v[112:115], v[152:155], v[168:171], v[112:115]
	v_mfma_f32_16x16x32_bf16 v[100:103], v[144:147], v[186:189], v[100:103]
	v_mfma_f32_16x16x32_bf16 v[96:99], v[152:155], v[186:189], v[96:99]
	v_mfma_f32_16x16x32_bf16 v[84:87], v[144:147], v[196:199], v[84:87]
	v_mfma_f32_16x16x32_bf16 v[80:83], v[152:155], v[196:199], v[80:83]
	v_mfma_f32_16x16x32_bf16 v[132:135], v[148:151], v[164:167], v[132:135]
	v_mfma_f32_16x16x32_bf16 v[128:131], v[156:159], v[164:167], v[128:131]
	v_mfma_f32_16x16x32_bf16 v[116:119], v[148:151], v[172:175], v[116:119]
	v_mfma_f32_16x16x32_bf16 v[112:115], v[156:159], v[172:175], v[112:115]
	v_mfma_f32_16x16x32_bf16 v[100:103], v[148:151], v[190:193], v[100:103]
	v_mfma_f32_16x16x32_bf16 v[96:99], v[156:159], v[190:193], v[96:99]
	v_mfma_f32_16x16x32_bf16 v[84:87], v[148:151], v[200:203], v[84:87]
	v_mfma_f32_16x16x32_bf16 v[80:83], v[156:159], v[200:203], v[80:83]
	s_setprio 0
	s_barrier
; #define PG8_STAGE(bufoff, gbase, voff) do { _Pragma("unroll") for (int _i = 0; _i < 2; ++_i) \
;         __builtin_amdgcn_global_load_lds((const unsigned*)((const char*)(gbase) + (voff)[_i]), (PG8_LAS unsigned*)(lds + (bufoff) + ldsw + _i * 8192), 16, 0, 0); } while (0)
; #define PG8_LDA(dst, b, h) do { _Pragma("unroll") for (int m = 0; m < 4; ++m) _Pragma("unroll") for (int k = 0; k < 2; ++k) dst[m][k] = *(const PG8_LAS bf16x8*)(lds + PG8_SA(b, h) + aoff + m * 2048 + k * 1024); } while (0)
; #define PG8_MMA(ai, bj, At, Bt) do { __builtin_amdgcn_s_setprio(1); _Pragma("unroll") for (int m = 0; m < 4; ++m) _Pragma("unroll") for (int n = 0; n < 2; ++n) _Pragma("unroll") for (int k = 0; k < 2; ++k) \
;         acc[ai][bj][m][n] = __builtin_amdgcn_mfma_f32_16x16x32_bf16(Bt[n][k], At[m][k], acc[ai][bj][m][n], 0, 0, 0); __builtin_amdgcn_s_setprio(0); } while (0)
; #define PG8_WAIT_V(n) asm volatile("s_waitcnt vmcnt(" #n ")" ::: "memory")
; #define PG8_WAIT_L(n) asm volatile("s_waitcnt lgkmcnt(" #n ")" ::: "memory")
; #define PG8_BAR __builtin_amdgcn_s_barrier()
; #define PG8_SCHED __builtin_amdgcn_sched_barrier(0)
; template <class Epi, class Sched, bool ALIGN_EPI = false, bool SP2 = false>
; __device__ __forceinline__ void gemm_phase(PG8_LAS unsigned char* lds, const Gemm g, const Sched& S, const Epi& E) {
;     ...
;             PG8_LDA(At, 1, 1); PG8_STAGE(PG8_SB(1, 0), b3, voffB); PG8_STAGE(PG8_SB(1, 1), b3 + hstep, voffB); PG8_STAGE(PG8_SA(1, 0), a3, voffA);
;             PG8_WAIT_V(8); PG8_WAIT_L(0); PG8_BAR; PG8_MMA(1, 0, At, B0); PG8_MMA(1, 1, At, B1); PG8_BAR; PG8_SCHED;
;     ...
;         }
;         if constexpr (ALIGN_EPI) { if (wr == 0) PG8_BAR; }
	s_add_i32 s12, s12, s2
	v_lshl_add_u64 v[204:205], v[204:205], 0, s[30:31]
	s_mov_b32 m0, s12
	ds_read_b128 v[160:163], v237 offset:49152
	ds_read_b128 v[164:167], v237 offset:50176
	ds_read_b128 v[168:171], v237 offset:51200
	ds_read_b128 v[172:175], v237 offset:52224
	ds_read_b128 v[186:189], v237 offset:53248
	ds_read_b128 v[190:193], v237 offset:54272
	ds_read_b128 v[196:199], v237 offset:55296
	ds_read_b128 v[200:203], v237 offset:56320
	global_load_lds_dwordx4 v[204:205], off
	v_lshl_add_u64 v[204:205], v[206:207], 0, s[30:31]
	s_add_i32 m0, s12, 0x2000
	s_add_i32 s12, s29, s2
	global_load_lds_dwordx4 v[204:205], off
	v_lshl_add_u64 v[204:205], v[208:209], 0, s[30:31]
	s_mov_b32 m0, s12
	s_nop 0
	global_load_lds_dwordx4 v[204:205], off
	v_lshl_add_u64 v[204:205], v[210:211], 0, s[30:31]
	s_add_i32 m0, s12, 0x2000
	s_nop 0
	global_load_lds_dwordx4 v[204:205], off
	v_lshl_add_u64 v[204:205], v[212:213], 0, s[30:31]
	s_mov_b32 m0, s48
	s_nop 0
	global_load_lds_dwordx4 v[204:205], off
	v_lshl_add_u64 v[204:205], v[222:223], 0, s[30:31]
	s_mov_b32 m0, s49
	s_nop 0
	global_load_lds_dwordx4 v[204:205], off
	s_waitcnt vmcnt(8)
	s_waitcnt lgkmcnt(0)
	s_barrier
	s_setprio 1
	s_waitcnt lgkmcnt(0)
	v_mfma_f32_16x16x32_bf16 v[76:79], v[56:59], v[160:163], v[76:79]
	v_mfma_f32_16x16x32_bf16 v[72:75], v[64:67], v[160:163], v[72:75]
	v_mfma_f32_16x16x32_bf16 v[44:47], v[56:59], v[168:171], v[44:47]
	v_mfma_f32_16x16x32_bf16 v[40:43], v[64:67], v[168:171], v[40:43]
	v_mfma_f32_16x16x32_bf16 v[28:31], v[56:59], v[186:189], v[28:31]
	v_mfma_f32_16x16x32_bf16 v[24:27], v[64:67], v[186:189], v[24:27]
	v_mfma_f32_16x16x32_bf16 v[12:15], v[56:59], v[196:199], v[12:15]
	v_mfma_f32_16x16x32_bf16 v[8:11], v[64:67], v[196:199], v[8:11]
	v_mfma_f32_16x16x32_bf16 v[76:79], v[60:63], v[164:167], v[76:79]
	v_mfma_f32_16x16x32_bf16 v[72:75], v[68:71], v[164:167], v[72:75]
	v_mfma_f32_16x16x32_bf16 v[44:47], v[60:63], v[172:175], v[44:47]
	v_mfma_f32_16x16x32_bf16 v[40:43], v[68:71], v[172:175], v[40:43]
	v_mfma_f32_16x16x32_bf16 v[28:31], v[60:63], v[190:193], v[28:31]
	v_mfma_f32_16x16x32_bf16 v[24:27], v[68:71], v[190:193], v[24:27]
	v_mfma_f32_16x16x32_bf16 v[12:15], v[60:63], v[200:203], v[12:15]
	v_mfma_f32_16x16x32_bf16 v[8:11], v[68:71], v[200:203], v[8:11]
	v_mfma_f32_16x16x32_bf16 v[52:55], v[144:147], v[160:163], v[52:55]
	v_mfma_f32_16x16x32_bf16 v[48:51], v[152:155], v[160:163], v[48:51]
	v_mfma_f32_16x16x32_bf16 v[36:39], v[144:147], v[168:171], v[36:39]
	v_mfma_f32_16x16x32_bf16 v[32:35], v[152:155], v[168:171], v[32:35]
	v_mfma_f32_16x16x32_bf16 v[20:23], v[144:147], v[186:189], v[20:23]
	v_mfma_f32_16x16x32_bf16 v[16:19], v[152:155], v[186:189], v[16:19]
	v_mfma_f32_16x16x32_bf16 v[4:7], v[144:147], v[196:199], v[4:7]
	v_mfma_f32_16x16x32_bf16 v[0:3], v[152:155], v[196:199], v[0:3]
	v_mfma_f32_16x16x32_bf16 v[52:55], v[148:151], v[164:167], v[52:55]
	v_mfma_f32_16x16x32_bf16 v[48:51], v[156:159], v[164:167], v[48:51]
	v_mfma_f32_16x16x32_bf16 v[36:39], v[148:151], v[172:175], v[36:39]
	v_mfma_f32_16x16x32_bf16 v[32:35], v[156:159], v[172:175], v[32:35]
	v_mfma_f32_16x16x32_bf16 v[20:23], v[148:151], v[190:193], v[20:23]
	v_mfma_f32_16x16x32_bf16 v[16:19], v[156:159], v[190:193], v[16:19]
	v_mfma_f32_16x16x32_bf16 v[4:7], v[148:151], v[200:203], v[4:7]
	v_mfma_f32_16x16x32_bf16 v[0:3], v[156:159], v[200:203], v[0:3]
	s_setprio 0
	s_barrier
	s_add_u32 s44, s44, 0x100
	s_addc_u32 s45, s45, 0
	s_add_u32 vcc_lo, vcc_lo, 0x100
	s_addc_u32 vcc_hi, vcc_hi, 0
	s_cmp_ge_u32 s28, s7
	s_mov_b32 s46, s28
	s_cbranch_scc0 .LBB0_82
	s_and_b64 vcc, exec, s[50:51]
	s_cbranch_vccz .LBB0_85
	s_barrier

; #define PG8_STAGE(bufoff, gbase, voff) do { _Pragma("unroll") for (int _i = 0; _i < 2; ++_i) \
;         __builtin_amdgcn_global_load_lds((const unsigned*)((const char*)(gbase) + (voff)[_i]), (PG8_LAS unsigned*)(lds + (bufoff) + ldsw + _i * 8192), 16, 0, 0); } while (0)
; #define PG8_LDA(dst, b, h) do { _Pragma("unroll") for (int m = 0; m < 4; ++m) _Pragma("unroll") for (int k = 0; k < 2; ++k) dst[m][k] = *(const PG8_LAS bf16x8*)(lds + PG8_SA(b, h) + aoff + m * 2048 + k * 1024); } while (0)
; #define PG8_LDB(dst, b, h) do { _Pragma("unroll") for (int n = 0; n < 2; ++n) _Pragma("unroll") for (int k = 0; k < 2; ++k) dst[n][k] = *(const PG8_LAS bf16x8*)(lds + PG8_SB(b, h) + boff + n * 2048 + k * 1024); } while (0)
; #define PG8_MMA(ai, bj, At, Bt) do { __builtin_amdgcn_s_setprio(1); _Pragma("unroll") for (int m = 0; m < 4; ++m) _Pragma("unroll") for (int n = 0; n < 2; ++n) _Pragma("unroll") for (int k = 0; k < 2; ++k) \
;         acc[ai][bj][m][n] = __builtin_amdgcn_mfma_f32_16x16x32_bf16(Bt[n][k], At[m][k], acc[ai][bj][m][n], 0, 0, 0); __builtin_amdgcn_s_setprio(0); } while (0)
; #define PG8_WAIT_V(n) asm volatile("s_waitcnt vmcnt(" #n ")" ::: "memory")
; #define PG8_BAR __builtin_amdgcn_s_barrier()
; template <class Epi, class Sched, bool ALIGN_EPI = false, bool SP2 = false>
; __device__ __forceinline__ void gemm_phase(PG8_LAS unsigned char* lds, const Gemm g, const Sched& S, const Epi& E) {
;     ...
;         for (int t = 0; t < nt; t += 2) {
;             const bool last = (t == nt - 2);
;             const char* a1 = cA + (size_t)(t + 1) * kstep;
;             const char* a2 = last ? nA : cA + (size_t)(t + 2) * kstep; const char* b2 = last ? nB : cB + (size_t)(t + 2) * kstep;
;             const char* a3 = a2 + kstep; const char* b3 = b2 + kstep;
;             if (last && has_next) S.a_ready(nxt);
;             if constexpr (SP2) {
;             PG8_LDB(B0, 0, 0); PG8_LDB(B1, 0, 1); PG8_SCHED; PG8_LDA(At, 0, 0); PG8_STAGE(PG8_SA(1, 1), a1 + hstep, voffA);
;             PG8_WAIT_V(8); PG8_WAIT_L(0); PG8_BAR; PG8_MMA(0, 0, At, B0); PG8_MMA(0, 1, At, B1); PG8_BAR; PG8_SCHED;
;             PG8_LDA(At, 0, 1); PG8_STAGE(PG8_SB(0, 0), b2, voffB); PG8_STAGE(PG8_SB(0, 1), b2 + hstep, voffB); PG8_STAGE(PG8_SA(0, 0), a2, voffA);
;             PG8_WAIT_V(8); PG8_WAIT_L(0); PG8_BAR; PG8_MMA(1, 0, At, B0); PG8_MMA(1, 1, At, B1); PG8_BAR; PG8_SCHED;
.LBB0_402:
	s_add_u32 s28, s26, 0xfff80080
	s_addc_u32 s29, s27, -1
	s_add_i32 s72, 0, 0x10000
	s_cmp_eq_u32 s88, 28
	s_cselect_b32 s49, s50, s29
	s_cselect_b32 s48, s51, s28
	s_cselect_b32 s47, s52, s61
	s_cselect_b32 s46, s53, s55
	s_add_i32 s73, 0, 0x14000
	v_add_u32_e32 v44, s72, v172
	v_add_u32_e32 v175, s73, v172
	ds_read_b128 v[32:35], v44
	ds_read_b128 v[36:39], v44 offset:1024
	ds_read_b128 v[40:43], v44 offset:2048
	ds_read_b128 v[44:47], v44 offset:3072
	ds_read_b128 v[160:163], v175
	ds_read_b128 v[164:167], v175 offset:1024
	ds_read_b128 v[168:171], v175 offset:2048
	ds_read_b128 v[176:179], v175 offset:3072
	v_lshl_add_u64 v[192:193], s[26:27], 0, v[156:157]
	s_add_i32 m0, s77, 0xc000
	ds_read_b128 v[180:183], v174
	ds_read_b128 v[184:187], v174 offset:1024
	ds_read_b128 v[188:191], v174 offset:2048
	ds_read_b128 v[196:199], v174 offset:3072
	ds_read_b128 v[200:203], v174 offset:4096
	ds_read_b128 v[204:207], v174 offset:5120
	ds_read_b128 v[208:211], v174 offset:6144
	ds_read_b128 v[234:237], v174 offset:7168
	global_load_lds_dwordx4 v[192:193], off
	v_lshl_add_u64 v[192:193], s[26:27], 0, v[158:159]
	s_add_i32 m0, s77, 0xe000
	s_nop 0
	global_load_lds_dwordx4 v[192:193], off
	s_waitcnt vmcnt(8)
	s_waitcnt lgkmcnt(0)
	s_barrier
	s_setprio 1
	s_waitcnt lgkmcnt(0)
	v_mfma_f32_16x16x32_bf16 v[140:143], v[32:35], v[180:183], v[140:143]
	v_mfma_f32_16x16x32_bf16 v[136:139], v[40:43], v[180:183], v[136:139]
	v_mfma_f32_16x16x32_bf16 v[124:127], v[32:35], v[188:191], v[124:127]
	v_mfma_f32_16x16x32_bf16 v[120:123], v[40:43], v[188:191], v[120:123]
	v_mfma_f32_16x16x32_bf16 v[108:111], v[32:35], v[200:203], v[108:111]
	v_mfma_f32_16x16x32_bf16 v[104:107], v[40:43], v[200:203], v[104:107]
	v_mfma_f32_16x16x32_bf16 v[92:95], v[32:35], v[208:211], v[92:95]
	v_mfma_f32_16x16x32_bf16 v[88:91], v[40:43], v[208:211], v[88:91]
	v_mfma_f32_16x16x32_bf16 v[140:143], v[36:39], v[184:187], v[140:143]
	v_mfma_f32_16x16x32_bf16 v[136:139], v[44:47], v[184:187], v[136:139]
	v_mfma_f32_16x16x32_bf16 v[124:127], v[36:39], v[196:199], v[124:127]
	v_mfma_f32_16x16x32_bf16 v[120:123], v[44:47], v[196:199], v[120:123]
	v_mfma_f32_16x16x32_bf16 v[108:111], v[36:39], v[204:207], v[108:111]
	v_mfma_f32_16x16x32_bf16 v[104:107], v[44:47], v[204:207], v[104:107]
	v_mfma_f32_16x16x32_bf16 v[92:95], v[36:39], v[234:237], v[92:95]
	v_mfma_f32_16x16x32_bf16 v[88:91], v[44:47], v[234:237], v[88:91]
	v_mfma_f32_16x16x32_bf16 v[132:135], v[160:163], v[180:183], v[132:135]
	v_mfma_f32_16x16x32_bf16 v[128:131], v[168:171], v[180:183], v[128:131]
	v_mfma_f32_16x16x32_bf16 v[116:119], v[160:163], v[188:191], v[116:119]
	v_mfma_f32_16x16x32_bf16 v[112:115], v[168:171], v[188:191], v[112:115]
	v_mfma_f32_16x16x32_bf16 v[100:103], v[160:163], v[200:203], v[100:103]
	v_mfma_f32_16x16x32_bf16 v[96:99], v[168:171], v[200:203], v[96:99]
	v_mfma_f32_16x16x32_bf16 v[84:87], v[160:163], v[208:211], v[84:87]
	v_mfma_f32_16x16x32_bf16 v[80:83], v[168:171], v[208:211], v[80:83]
	v_mfma_f32_16x16x32_bf16 v[132:135], v[164:167], v[184:187], v[132:135]
	v_mfma_f32_16x16x32_bf16 v[128:131], v[176:179], v[184:187], v[128:131]
	v_mfma_f32_16x16x32_bf16 v[116:119], v[164:167], v[196:199], v[116:119]
	v_mfma_f32_16x16x32_bf16 v[112:115], v[176:179], v[196:199], v[112:115]
	v_mfma_f32_16x16x32_bf16 v[100:103], v[164:167], v[204:207], v[100:103]
	v_mfma_f32_16x16x32_bf16 v[96:99], v[176:179], v[204:207], v[96:99]
	v_mfma_f32_16x16x32_bf16 v[84:87], v[164:167], v[234:237], v[84:87]
	v_mfma_f32_16x16x32_bf16 v[80:83], v[176:179], v[234:237], v[80:83]
	s_setprio 0
	s_barrier
	s_add_i32 s28, s72, s76
	v_lshl_add_u64 v[192:193], s[46:47], 0, v[148:149]
	s_mov_b32 m0, s28
	ds_read_b128 v[180:183], v174 offset:16384
	ds_read_b128 v[184:187], v174 offset:17408
	ds_read_b128 v[188:191], v174 offset:18432
	ds_read_b128 v[196:199], v174 offset:19456
	ds_read_b128 v[200:203], v174 offset:20480
	ds_read_b128 v[204:207], v174 offset:21504
	ds_read_b128 v[208:211], v174 offset:22528
	ds_read_b128 v[234:237], v174 offset:23552
	global_load_lds_dwordx4 v[192:193], off
	s_add_i32 m0, s28, 0x2000
	s_add_u32 s28, s46, 0x80000
	v_lshl_add_u64 v[212:213], s[46:47], 0, v[144:145]
	s_addc_u32 s29, s47, 0
	s_add_i32 s72, s73, s76
	global_load_lds_dwordx4 v[212:213], off
	v_lshl_add_u64 v[222:223], s[28:29], 0, v[148:149]
	s_mov_b32 m0, s72
	v_lshl_add_u64 v[224:225], s[48:49], 0, v[146:147]
	global_load_lds_dwordx4 v[222:223], off
	v_lshl_add_u64 v[222:223], s[28:29], 0, v[144:145]
	s_add_i32 m0, s72, 0x2000
	s_nop 0
	global_load_lds_dwordx4 v[222:223], off
	v_lshl_add_u64 v[222:223], s[48:49], 0, v[150:151]
	s_mov_b32 m0, s77
	s_nop 0
	global_load_lds_dwordx4 v[222:223], off
	s_mov_b32 m0, s79
	s_nop 0
	global_load_lds_dwordx4 v[224:225], off
	s_waitcnt vmcnt(8)
	s_waitcnt lgkmcnt(0)
	s_barrier
; #define PG8_STAGE(bufoff, gbase, voff) do { _Pragma("unroll") for (int _i = 0; _i < 2; ++_i) \
;         __builtin_amdgcn_global_load_lds((const unsigned*)((const char*)(gbase) + (voff)[_i]), (PG8_LAS unsigned*)(lds + (bufoff) + ldsw + _i * 8192), 16, 0, 0); } while (0)
; #define PG8_LDA(dst, b, h) do { _Pragma("unroll") for (int m = 0; m < 4; ++m) _Pragma("unroll") for (int k = 0; k < 2; ++k) dst[m][k] = *(const PG8_LAS bf16x8*)(lds + PG8_SA(b, h) + aoff + m * 2048 + k * 1024); } while (0)
; #define PG8_LDB(dst, b, h) do { _Pragma("unroll") for (int n = 0; n < 2; ++n) _Pragma("unroll") for (int k = 0; k < 2; ++k) dst[n][k] = *(const PG8_LAS bf16x8*)(lds + PG8_SB(b, h) + boff + n * 2048 + k * 1024); } while (0)
; #define PG8_MMA(ai, bj, At, Bt) do { __builtin_amdgcn_s_setprio(1); _Pragma("unroll") for (int m = 0; m < 4; ++m) _Pragma("unroll") for (int n = 0; n < 2; ++n) _Pragma("unroll") for (int k = 0; k < 2; ++k) \
;         acc[ai][bj][m][n] = __builtin_amdgcn_mfma_f32_16x16x32_bf16(Bt[n][k], At[m][k], acc[ai][bj][m][n], 0, 0, 0); __builtin_amdgcn_s_setprio(0); } while (0)
; #define PG8_WAIT_V(n) asm volatile("s_waitcnt vmcnt(" #n ")" ::: "memory")
; #define PG8_WAIT_L(n) asm volatile("s_waitcnt lgkmcnt(" #n ")" ::: "memory")
; #define PG8_BAR __builtin_amdgcn_s_barrier()
; #define PG8_SCHED __builtin_amdgcn_sched_barrier(0)
; template <class Epi, class Sched, bool ALIGN_EPI = false, bool SP2 = false>
; __device__ __forceinline__ void gemm_phase(PG8_LAS unsigned char* lds, const Gemm g, const Sched& S, const Epi& E) {
;     ...
;             PG8_WAIT_V(8); PG8_WAIT_L(0); PG8_BAR; PG8_MMA(1, 0, At, B0); PG8_MMA(1, 1, At, B1); PG8_BAR; PG8_SCHED;
;             PG8_LDB(B0, 1, 0); PG8_LDB(B1, 1, 1); PG8_SCHED; PG8_LDA(At, 1, 0); PG8_STAGE(PG8_SA(0, 1), a2 + hstep, voffA);
;             PG8_WAIT_V(8); PG8_WAIT_L(0); PG8_BAR; PG8_MMA(0, 0, At, B0); PG8_MMA(0, 1, At, B1); PG8_BAR; PG8_SCHED;
	s_setprio 1
	s_waitcnt lgkmcnt(0)
	v_mfma_f32_16x16x32_bf16 v[76:79], v[32:35], v[180:183], v[76:79]
	v_mfma_f32_16x16x32_bf16 v[72:75], v[40:43], v[180:183], v[72:75]
	v_mfma_f32_16x16x32_bf16 v[60:63], v[32:35], v[188:191], v[60:63]
	v_mfma_f32_16x16x32_bf16 v[56:59], v[40:43], v[188:191], v[56:59]
	v_mfma_f32_16x16x32_bf16 v[28:31], v[32:35], v[200:203], v[28:31]
	v_mfma_f32_16x16x32_bf16 v[24:27], v[40:43], v[200:203], v[24:27]
	v_mfma_f32_16x16x32_bf16 v[12:15], v[32:35], v[208:211], v[12:15]
	v_mfma_f32_16x16x32_bf16 v[8:11], v[40:43], v[208:211], v[8:11]
	v_mfma_f32_16x16x32_bf16 v[76:79], v[36:39], v[184:187], v[76:79]
	v_mfma_f32_16x16x32_bf16 v[72:75], v[44:47], v[184:187], v[72:75]
	v_mfma_f32_16x16x32_bf16 v[60:63], v[36:39], v[196:199], v[60:63]
	v_mfma_f32_16x16x32_bf16 v[56:59], v[44:47], v[196:199], v[56:59]
	v_mfma_f32_16x16x32_bf16 v[28:31], v[36:39], v[204:207], v[28:31]
	v_mfma_f32_16x16x32_bf16 v[24:27], v[44:47], v[204:207], v[24:27]
	v_mfma_f32_16x16x32_bf16 v[12:15], v[36:39], v[234:237], v[12:15]
	v_mfma_f32_16x16x32_bf16 v[8:11], v[44:47], v[234:237], v[8:11]
	v_mfma_f32_16x16x32_bf16 v[20:23], v[160:163], v[200:203], v[20:23]
	v_mfma_f32_16x16x32_bf16 v[16:19], v[168:171], v[200:203], v[16:19]
	v_mfma_f32_16x16x32_bf16 v[4:7], v[160:163], v[208:211], v[4:7]
	v_mfma_f32_16x16x32_bf16 v[0:3], v[168:171], v[208:211], v[0:3]
	v_mfma_f32_16x16x32_bf16 v[32:35], v[160:163], v[180:183], v[68:71]
	v_mfma_f32_16x16x32_bf16 v[36:39], v[168:171], v[180:183], v[64:67]
	v_mfma_f32_16x16x32_bf16 v[40:43], v[160:163], v[188:191], v[52:55]
	v_mfma_f32_16x16x32_bf16 v[44:47], v[168:171], v[188:191], v[48:51]
	v_mfma_f32_16x16x32_bf16 v[20:23], v[164:167], v[204:207], v[20:23]
	v_mfma_f32_16x16x32_bf16 v[16:19], v[176:179], v[204:207], v[16:19]
	v_mfma_f32_16x16x32_bf16 v[4:7], v[164:167], v[234:237], v[4:7]
	v_mfma_f32_16x16x32_bf16 v[0:3], v[176:179], v[234:237], v[0:3]
	v_mfma_f32_16x16x32_bf16 v[32:35], v[164:167], v[184:187], v[32:35]
	v_mfma_f32_16x16x32_bf16 v[36:39], v[176:179], v[184:187], v[36:39]
	v_mfma_f32_16x16x32_bf16 v[40:43], v[164:167], v[196:199], v[40:43]
	v_mfma_f32_16x16x32_bf16 v[44:47], v[176:179], v[196:199], v[44:47]
	s_setprio 0
	s_barrier
	s_add_i32 s72, 0, 0x18000
	s_add_i32 s73, 0, 0x1c000
	v_add_u32_e32 v68, s72, v172
	v_add_u32_e32 v175, s73, v172
	ds_read_b128 v[48:51], v68
	ds_read_b128 v[52:55], v68 offset:1024
	ds_read_b128 v[64:67], v68 offset:2048
	ds_read_b128 v[68:71], v68 offset:3072
	ds_read_b128 v[160:163], v175
	ds_read_b128 v[164:167], v175 offset:1024
	ds_read_b128 v[168:171], v175 offset:2048
	ds_read_b128 v[176:179], v175 offset:3072
	s_add_u32 s28, s48, 0x80000
	s_addc_u32 s29, s49, 0
	s_mov_b32 m0, s80
	v_lshl_add_u64 v[228:229], s[28:29], 0, v[150:151]
	ds_read_b128 v[180:183], v174 offset:32768
	ds_read_b128 v[184:187], v174 offset:33792
	ds_read_b128 v[188:191], v174 offset:34816
	ds_read_b128 v[196:199], v174 offset:35840
	ds_read_b128 v[200:203], v174 offset:36864
	ds_read_b128 v[204:207], v174 offset:37888
	ds_read_b128 v[208:211], v174 offset:38912
	ds_read_b128 v[234:237], v174 offset:39936
	global_load_lds_dwordx4 v[228:229], off
	v_lshl_add_u64 v[228:229], s[28:29], 0, v[146:147]
	s_mov_b32 m0, s12
	s_nop 0
	global_load_lds_dwordx4 v[228:229], off
	s_waitcnt vmcnt(8)
	s_waitcnt lgkmcnt(0)
	s_barrier
	s_setprio 1
	s_waitcnt lgkmcnt(0)
	v_mfma_f32_16x16x32_bf16 v[140:143], v[48:51], v[180:183], v[140:143]
	v_mfma_f32_16x16x32_bf16 v[136:139], v[64:67], v[180:183], v[136:139]
	v_mfma_f32_16x16x32_bf16 v[124:127], v[48:51], v[188:191], v[124:127]
	v_mfma_f32_16x16x32_bf16 v[120:123], v[64:67], v[188:191], v[120:123]
	v_mfma_f32_16x16x32_bf16 v[108:111], v[48:51], v[200:203], v[108:111]
	v_mfma_f32_16x16x32_bf16 v[104:107], v[64:67], v[200:203], v[104:107]
	v_mfma_f32_16x16x32_bf16 v[92:95], v[48:51], v[208:211], v[92:95]
	v_mfma_f32_16x16x32_bf16 v[88:91], v[64:67], v[208:211], v[88:91]
	v_mfma_f32_16x16x32_bf16 v[140:143], v[52:55], v[184:187], v[140:143]
	v_mfma_f32_16x16x32_bf16 v[136:139], v[68:71], v[184:187], v[136:139]
	v_mfma_f32_16x16x32_bf16 v[124:127], v[52:55], v[196:199], v[124:127]
	v_mfma_f32_16x16x32_bf16 v[120:123], v[68:71], v[196:199], v[120:123]
	v_mfma_f32_16x16x32_bf16 v[108:111], v[52:55], v[204:207], v[108:111]
	v_mfma_f32_16x16x32_bf16 v[104:107], v[68:71], v[204:207], v[104:107]
	v_mfma_f32_16x16x32_bf16 v[92:95], v[52:55], v[234:237], v[92:95]
	v_mfma_f32_16x16x32_bf16 v[88:91], v[68:71], v[234:237], v[88:91]
	v_mfma_f32_16x16x32_bf16 v[132:135], v[160:163], v[180:183], v[132:135]
	v_mfma_f32_16x16x32_bf16 v[128:131], v[168:171], v[180:183], v[128:131]
	v_mfma_f32_16x16x32_bf16 v[116:119], v[160:163], v[188:191], v[116:119]
	v_mfma_f32_16x16x32_bf16 v[112:115], v[168:171], v[188:191], v[112:115]
	v_mfma_f32_16x16x32_bf16 v[100:103], v[160:163], v[200:203], v[100:103]
	v_mfma_f32_16x16x32_bf16 v[96:99], v[168:171], v[200:203], v[96:99]
	v_mfma_f32_16x16x32_bf16 v[84:87], v[160:163], v[208:211], v[84:87]
	v_mfma_f32_16x16x32_bf16 v[80:83], v[168:171], v[208:211], v[80:83]
	v_mfma_f32_16x16x32_bf16 v[132:135], v[164:167], v[184:187], v[132:135]
	v_mfma_f32_16x16x32_bf16 v[128:131], v[176:179], v[184:187], v[128:131]
	v_mfma_f32_16x16x32_bf16 v[116:119], v[164:167], v[196:199], v[116:119]
	v_mfma_f32_16x16x32_bf16 v[112:115], v[176:179], v[196:199], v[112:115]
	v_mfma_f32_16x16x32_bf16 v[100:103], v[164:167], v[204:207], v[100:103]
	v_mfma_f32_16x16x32_bf16 v[96:99], v[176:179], v[204:207], v[96:99]
	v_mfma_f32_16x16x32_bf16 v[84:87], v[164:167], v[234:237], v[84:87]
	v_mfma_f32_16x16x32_bf16 v[80:83], v[176:179], v[234:237], v[80:83]
	s_setprio 0
	s_barrier
; #define PG8_STAGE(bufoff, gbase, voff) do { _Pragma("unroll") for (int _i = 0; _i < 2; ++_i) \
;         __builtin_amdgcn_global_load_lds((const unsigned*)((const char*)(gbase) + (voff)[_i]), (PG8_LAS unsigned*)(lds + (bufoff) + ldsw + _i * 8192), 16, 0, 0); } while (0)
; #define PG8_LDA(dst, b, h) do { _Pragma("unroll") for (int m = 0; m < 4; ++m) _Pragma("unroll") for (int k = 0; k < 2; ++k) dst[m][k] = *(const PG8_LAS bf16x8*)(lds + PG8_SA(b, h) + aoff + m * 2048 + k * 1024); } while (0)
; #define PG8_MMA(ai, bj, At, Bt) do { __builtin_amdgcn_s_setprio(1); _Pragma("unroll") for (int m = 0; m < 4; ++m) _Pragma("unroll") for (int n = 0; n < 2; ++n) _Pragma("unroll") for (int k = 0; k < 2; ++k) \
;         acc[ai][bj][m][n] = __builtin_amdgcn_mfma_f32_16x16x32_bf16(Bt[n][k], At[m][k], acc[ai][bj][m][n], 0, 0, 0); __builtin_amdgcn_s_setprio(0); } while (0)
; #define PG8_WAIT_V(n) asm volatile("s_waitcnt vmcnt(" #n ")" ::: "memory")
; #define PG8_WAIT_L(n) asm volatile("s_waitcnt lgkmcnt(" #n ")" ::: "memory")
; #define PG8_BAR __builtin_amdgcn_s_barrier()
; #define PG8_SCHED __builtin_amdgcn_sched_barrier(0)
; template <class Epi, class Sched, bool ALIGN_EPI = false, bool SP2 = false>
; __device__ __forceinline__ void gemm_phase(PG8_LAS unsigned char* lds, const Gemm g, const Sched& S, const Epi& E) {
;     ...
;             PG8_LDA(At, 1, 1); PG8_STAGE(PG8_SB(1, 0), b3, voffB); PG8_STAGE(PG8_SB(1, 1), b3 + hstep, voffB); PG8_STAGE(PG8_SA(1, 0), a3, voffA);
;             PG8_WAIT_V(8); PG8_WAIT_L(0); PG8_BAR; PG8_MMA(1, 0, At, B0); PG8_MMA(1, 1, At, B1); PG8_BAR; PG8_SCHED;
;     ...
;         }
;         if constexpr (ALIGN_EPI) { if (wr == 0) PG8_BAR; }
	s_add_i32 s28, s72, s76
	v_lshl_add_u64 v[192:193], v[192:193], 0, s[30:31]
	s_mov_b32 m0, s28
	ds_read_b128 v[180:183], v174 offset:49152
	ds_read_b128 v[184:187], v174 offset:50176
	ds_read_b128 v[188:191], v174 offset:51200
	ds_read_b128 v[196:199], v174 offset:52224
	ds_read_b128 v[200:203], v174 offset:53248
	ds_read_b128 v[204:207], v174 offset:54272
	ds_read_b128 v[208:211], v174 offset:55296
	ds_read_b128 v[234:237], v174 offset:56320
	global_load_lds_dwordx4 v[192:193], off
	s_add_i32 m0, s28, 0x2000
	s_add_u32 s28, s46, 0x80080
	v_lshl_add_u64 v[192:193], v[212:213], 0, s[30:31]
	s_addc_u32 s29, s47, 0
	s_add_i32 s46, s73, s76
	global_load_lds_dwordx4 v[192:193], off
	v_lshl_add_u64 v[192:193], s[28:29], 0, v[148:149]
	s_mov_b32 m0, s46
	s_nop 0
	global_load_lds_dwordx4 v[192:193], off
	v_lshl_add_u64 v[192:193], s[28:29], 0, v[144:145]
	s_add_i32 m0, s46, 0x2000
	s_nop 0
	global_load_lds_dwordx4 v[192:193], off
	v_lshl_add_u64 v[192:193], v[222:223], 0, s[30:31]
	s_mov_b32 m0, s78
	s_nop 0
	global_load_lds_dwordx4 v[192:193], off
	v_lshl_add_u64 v[192:193], v[224:225], 0, s[30:31]
	s_mov_b32 m0, s86
	s_nop 0
	global_load_lds_dwordx4 v[192:193], off
	s_waitcnt vmcnt(8)
	s_waitcnt lgkmcnt(0)
	s_barrier
	s_setprio 1
	s_waitcnt lgkmcnt(0)
	v_mfma_f32_16x16x32_bf16 v[76:79], v[48:51], v[180:183], v[76:79]
	v_mfma_f32_16x16x32_bf16 v[72:75], v[64:67], v[180:183], v[72:75]
	v_mfma_f32_16x16x32_bf16 v[60:63], v[48:51], v[188:191], v[60:63]
	v_mfma_f32_16x16x32_bf16 v[56:59], v[64:67], v[188:191], v[56:59]
	v_mfma_f32_16x16x32_bf16 v[28:31], v[48:51], v[200:203], v[28:31]
	v_mfma_f32_16x16x32_bf16 v[24:27], v[64:67], v[200:203], v[24:27]
	v_mfma_f32_16x16x32_bf16 v[12:15], v[48:51], v[208:211], v[12:15]
	v_mfma_f32_16x16x32_bf16 v[8:11], v[64:67], v[208:211], v[8:11]
	v_mfma_f32_16x16x32_bf16 v[76:79], v[52:55], v[184:187], v[76:79]
	v_mfma_f32_16x16x32_bf16 v[72:75], v[68:71], v[184:187], v[72:75]
	v_mfma_f32_16x16x32_bf16 v[60:63], v[52:55], v[196:199], v[60:63]
	v_mfma_f32_16x16x32_bf16 v[56:59], v[68:71], v[196:199], v[56:59]
	v_mfma_f32_16x16x32_bf16 v[28:31], v[52:55], v[204:207], v[28:31]
	v_mfma_f32_16x16x32_bf16 v[24:27], v[68:71], v[204:207], v[24:27]
	v_mfma_f32_16x16x32_bf16 v[12:15], v[52:55], v[234:237], v[12:15]
	v_mfma_f32_16x16x32_bf16 v[8:11], v[68:71], v[234:237], v[8:11]
	v_mfma_f32_16x16x32_bf16 v[32:35], v[160:163], v[180:183], v[32:35]
	v_mfma_f32_16x16x32_bf16 v[68:71], v[164:167], v[184:187], v[32:35]
	v_mfma_f32_16x16x32_bf16 v[32:35], v[168:171], v[180:183], v[36:39]
	v_mfma_f32_16x16x32_bf16 v[64:67], v[176:179], v[184:187], v[32:35]
	v_mfma_f32_16x16x32_bf16 v[32:35], v[160:163], v[188:191], v[40:43]
	v_mfma_f32_16x16x32_bf16 v[52:55], v[164:167], v[196:199], v[32:35]
	v_mfma_f32_16x16x32_bf16 v[32:35], v[168:171], v[188:191], v[44:47]
	v_mfma_f32_16x16x32_bf16 v[20:23], v[160:163], v[200:203], v[20:23]
	v_mfma_f32_16x16x32_bf16 v[16:19], v[168:171], v[200:203], v[16:19]
	v_mfma_f32_16x16x32_bf16 v[4:7], v[160:163], v[208:211], v[4:7]
	v_mfma_f32_16x16x32_bf16 v[0:3], v[168:171], v[208:211], v[0:3]
	v_mfma_f32_16x16x32_bf16 v[48:51], v[176:179], v[196:199], v[32:35]
	v_mfma_f32_16x16x32_bf16 v[20:23], v[164:167], v[204:207], v[20:23]
	v_mfma_f32_16x16x32_bf16 v[16:19], v[176:179], v[204:207], v[16:19]
	v_mfma_f32_16x16x32_bf16 v[4:7], v[164:167], v[234:237], v[4:7]
	v_mfma_f32_16x16x32_bf16 v[0:3], v[176:179], v[234:237], v[0:3]
	s_setprio 0
	s_barrier
	s_add_i32 s88, s88, 2
	s_add_u32 s26, s26, 0x100
	s_addc_u32 s27, s27, 0
	s_add_u32 s55, s55, 0x100
	s_addc_u32 s61, s61, 0
	s_cmp_gt_u32 s88, 29
	s_cbranch_scc0 .LBB0_402
	s_and_b64 vcc, exec, s[22:23]
	s_cbranch_vccz .LBB0_405
	s_barrier
